# speedup vs baseline: 1.0082x; 1.0082x over previous
; #define WAIT_L(n) asm volatile("s_waitcnt lgkmcnt(" #n ")" ::: "memory")
; #define BAR __builtin_amdgcn_s_barrier()
; #define SCHED __builtin_amdgcn_sched_barrier(0)
; #define STAGE(P, BASE, br, kt) do { const char* _g = (const char*)((BASE) + (size_t)(br) * GK + (kt) * BK); \
;     __builtin_amdgcn_global_load_lds((const unsigned*)(_g + voff0), (unsigned*)((char*)(P) + tx * 16), 16, 0, 0); \
;     __builtin_amdgcn_global_load_lds((const unsigned*)(_g + voff1), (unsigned*)((char*)(P) + tx * 16 + 8192), 16, 0, 0); } while (0)
; #define LDA(dst, b, h) _Pragma("unroll") for (int m = 0; m < 4; ++m) _Pragma("unroll") for (int k = 0; k < 2; ++k) \
;     dst[m][k] = *reinterpret_cast<const bf16x8*>((char*)shm + abase + (((b) * 2 + (h)) * 16384 + (m * 2 + k) * 1024))
; #define LDB(dst, b, h) _Pragma("unroll") for (int n = 0; n < 2; ++n) _Pragma("unroll") for (int k = 0; k < 2; ++k) \
;     dst[n][k] = *reinterpret_cast<const bf16x8*>((char*)shm + bbase + (((b) * 2 + (h)) * 16384 + (n * 2 + k) * 1024))
; template <bool SWAP>
; __device__ __forceinline__ void gemm_main(const u16* __restrict__ A, const u16* __restrict__ Bt, int brow, int bcol,
;                                           u16* shm, f32x4 (&acc)[2][2][4][2]) {
;     ...
;   for (int t = 0; t < nt - 2; t += 2) {
;     LDB(B0, 0, 0); SCHED; LDA(At, 0, 0); STAGE(SA(1, 1), A, brow + HALF, t + 1);
;     WAIT_L(8); BAR; WAIT_L(0); MMA(0, 0, At, B0); BAR; SCHED;
;     LDB(B1, 0, 1); STAGE(SB(0, 0), Bt, bcol, t + 2);
;     BAR; WAIT_L(0); MMA(0, 1, At, B1); BAR;
;     LDA(At, 0, 1); STAGE(SA(0, 0), A, brow, t + 2);
;     BAR; WAIT_L(0); MMA(1, 0, At, B0); BAR; SCHED;
.LBB0_436:
	ds_read_b128 v[150:153], v138
	ds_read_b128 v[154:157], v138 offset:1024
	ds_read_b128 v[158:161], v138 offset:2048
	ds_read_b128 v[162:165], v138 offset:3072
	v_add_u32_e32 v192, 0, v139
	v_add_u32_e32 v148, 0xc000, v192
	v_lshl_add_u64 v[190:191], s[50:51], 0, v[132:133]
	v_readfirstlane_b32 s2, v148
	v_add_u32_e32 v149, 0xe000, v192
	v_lshl_add_u64 v[202:203], v[190:191], 0, s[82:83]
	s_mov_b32 m0, s2
	v_lshl_add_u64 v[232:233], s[50:51], 0, v[134:135]
	v_readfirstlane_b32 s2, v149
	ds_read_b128 v[166:169], v137
	ds_read_b128 v[170:173], v137 offset:1024
	ds_read_b128 v[174:177], v137 offset:2048
	ds_read_b128 v[178:181], v137 offset:3072
	ds_read_b128 v[182:185], v137 offset:4096
	ds_read_b128 v[186:189], v137 offset:5120
	ds_read_b128 v[194:197], v137 offset:6144
	ds_read_b128 v[198:201], v137 offset:7168
	global_load_lds_dwordx4 v[202:203], off
	v_lshl_add_u64 v[202:203], v[232:233], 0, s[82:83]
	s_mov_b32 m0, s2
	s_nop 0
	global_load_lds_dwordx4 v[202:203], off
	s_waitcnt lgkmcnt(8)
	s_barrier
	s_waitcnt lgkmcnt(0)
	s_setprio 1
	v_mfma_f32_16x16x32_bf16 v[124:127], v[150:153], v[166:169], v[124:127]
	v_mfma_f32_16x16x32_bf16 v[120:123], v[158:161], v[166:169], v[120:123]
	v_mfma_f32_16x16x32_bf16 v[116:119], v[150:153], v[174:177], v[116:119]
	v_mfma_f32_16x16x32_bf16 v[112:115], v[158:161], v[174:177], v[112:115]
	v_mfma_f32_16x16x32_bf16 v[108:111], v[150:153], v[182:185], v[108:111]
	v_mfma_f32_16x16x32_bf16 v[104:107], v[158:161], v[182:185], v[104:107]
	v_mfma_f32_16x16x32_bf16 v[100:103], v[150:153], v[194:197], v[100:103]
	v_mfma_f32_16x16x32_bf16 v[96:99], v[158:161], v[194:197], v[96:99]
	v_mfma_f32_16x16x32_bf16 v[124:127], v[154:157], v[170:173], v[124:127]
	v_mfma_f32_16x16x32_bf16 v[120:123], v[162:165], v[170:173], v[120:123]
	v_mfma_f32_16x16x32_bf16 v[116:119], v[154:157], v[178:181], v[116:119]
	v_mfma_f32_16x16x32_bf16 v[112:115], v[162:165], v[178:181], v[112:115]
	v_mfma_f32_16x16x32_bf16 v[108:111], v[154:157], v[186:189], v[108:111]
	v_mfma_f32_16x16x32_bf16 v[104:107], v[162:165], v[186:189], v[104:107]
	v_mfma_f32_16x16x32_bf16 v[100:103], v[154:157], v[198:201], v[100:103]
	v_mfma_f32_16x16x32_bf16 v[96:99], v[162:165], v[198:201], v[96:99]
	s_setprio 0
	s_barrier
	v_add_u32_e32 v223, s28, v139
	v_lshl_add_u64 v[234:235], s[50:51], 0, v[128:129]
	v_readfirstlane_b32 s2, v223
	v_lshl_add_u64 v[236:237], v[234:235], 0, s[74:75]
	s_mov_b32 m0, s2
	v_add_u32_e32 v223, 0x2000, v223
	ds_read_b128 v[202:205], v138 offset:16384
	ds_read_b128 v[206:209], v138 offset:17408
	ds_read_b128 v[224:227], v138 offset:18432
	ds_read_b128 v[228:231], v138 offset:19456
	global_load_lds_dwordx4 v[236:237], off
	v_lshl_add_u64 v[236:237], s[50:51], 0, v[130:131]
	v_readfirstlane_b32 s2, v223
	v_lshl_add_u64 v[238:239], v[236:237], 0, s[74:75]
	s_mov_b32 m0, s2
	s_nop 0
	global_load_lds_dwordx4 v[238:239], off
	s_barrier
	s_waitcnt lgkmcnt(0)
	s_setprio 1
	v_mfma_f32_16x16x32_bf16 v[92:95], v[202:205], v[166:169], v[92:95]
	v_mfma_f32_16x16x32_bf16 v[88:91], v[224:227], v[166:169], v[88:91]
	v_mfma_f32_16x16x32_bf16 v[84:87], v[202:205], v[174:177], v[84:87]
	v_mfma_f32_16x16x32_bf16 v[80:83], v[224:227], v[174:177], v[80:83]
	v_mfma_f32_16x16x32_bf16 v[76:79], v[202:205], v[182:185], v[76:79]
	v_mfma_f32_16x16x32_bf16 v[72:75], v[224:227], v[182:185], v[72:75]
	v_mfma_f32_16x16x32_bf16 v[68:71], v[202:205], v[194:197], v[68:71]
	v_mfma_f32_16x16x32_bf16 v[64:67], v[224:227], v[194:197], v[64:67]
	v_mfma_f32_16x16x32_bf16 v[92:95], v[206:209], v[170:173], v[92:95]
	v_mfma_f32_16x16x32_bf16 v[88:91], v[228:231], v[170:173], v[88:91]
	v_mfma_f32_16x16x32_bf16 v[84:87], v[206:209], v[178:181], v[84:87]
	v_mfma_f32_16x16x32_bf16 v[80:83], v[228:231], v[178:181], v[80:83]
	v_mfma_f32_16x16x32_bf16 v[76:79], v[206:209], v[186:189], v[76:79]
	v_mfma_f32_16x16x32_bf16 v[72:75], v[228:231], v[186:189], v[72:75]
	v_mfma_f32_16x16x32_bf16 v[68:71], v[206:209], v[198:201], v[68:71]
	v_mfma_f32_16x16x32_bf16 v[64:67], v[228:231], v[198:201], v[64:67]
	s_setprio 0
	s_barrier
	ds_read_b128 v[166:169], v137 offset:16384
	ds_read_b128 v[170:173], v137 offset:17408
	ds_read_b128 v[174:177], v137 offset:18432
	ds_read_b128 v[178:181], v137 offset:19456
	ds_read_b128 v[182:185], v137 offset:20480
	ds_read_b128 v[186:189], v137 offset:21504
	ds_read_b128 v[194:197], v137 offset:22528
	ds_read_b128 v[198:201], v137 offset:23552
	v_readfirstlane_b32 s2, v192
	v_add_u32_e32 v223, 0x2000, v192
	v_lshl_add_u64 v[238:239], v[190:191], 0, s[76:77]
	s_mov_b32 m0, s2
	v_readfirstlane_b32 s2, v223
	global_load_lds_dwordx4 v[238:239], off
	v_lshl_add_u64 v[238:239], v[232:233], 0, s[76:77]
	s_mov_b32 m0, s2
	s_nop 0
	global_load_lds_dwordx4 v[238:239], off
	s_barrier
	s_waitcnt lgkmcnt(0)
	s_setprio 1
	v_mfma_f32_16x16x32_bf16 v[60:63], v[150:153], v[166:169], v[60:63]
	v_mfma_f32_16x16x32_bf16 v[56:59], v[158:161], v[166:169], v[56:59]
	v_mfma_f32_16x16x32_bf16 v[52:55], v[150:153], v[174:177], v[52:55]
	v_mfma_f32_16x16x32_bf16 v[48:51], v[158:161], v[174:177], v[48:51]
	v_mfma_f32_16x16x32_bf16 v[44:47], v[150:153], v[182:185], v[44:47]
	v_mfma_f32_16x16x32_bf16 v[40:43], v[158:161], v[182:185], v[40:43]
	v_mfma_f32_16x16x32_bf16 v[36:39], v[150:153], v[194:197], v[36:39]
	v_mfma_f32_16x16x32_bf16 v[32:35], v[158:161], v[194:197], v[32:35]
	v_mfma_f32_16x16x32_bf16 v[60:63], v[154:157], v[170:173], v[60:63]
	v_mfma_f32_16x16x32_bf16 v[56:59], v[162:165], v[170:173], v[56:59]
	v_mfma_f32_16x16x32_bf16 v[52:55], v[154:157], v[178:181], v[52:55]
	v_mfma_f32_16x16x32_bf16 v[48:51], v[162:165], v[178:181], v[48:51]
	v_mfma_f32_16x16x32_bf16 v[44:47], v[154:157], v[186:189], v[44:47]
	v_mfma_f32_16x16x32_bf16 v[40:43], v[162:165], v[186:189], v[40:43]
	v_mfma_f32_16x16x32_bf16 v[36:39], v[154:157], v[198:201], v[36:39]
	v_mfma_f32_16x16x32_bf16 v[32:35], v[162:165], v[198:201], v[32:35]
	s_setprio 0
	s_barrier
; #define WAIT_V(n) asm volatile("s_waitcnt vmcnt(" #n ")" ::: "memory")
; #define WAIT_L(n) asm volatile("s_waitcnt lgkmcnt(" #n ")" ::: "memory")
; #define BAR __builtin_amdgcn_s_barrier()
; #define SCHED __builtin_amdgcn_sched_barrier(0)
; #define STAGE(P, BASE, br, kt) do { const char* _g = (const char*)((BASE) + (size_t)(br) * GK + (kt) * BK); \
;     __builtin_amdgcn_global_load_lds((const unsigned*)(_g + voff0), (unsigned*)((char*)(P) + tx * 16), 16, 0, 0); \
;     __builtin_amdgcn_global_load_lds((const unsigned*)(_g + voff1), (unsigned*)((char*)(P) + tx * 16 + 8192), 16, 0, 0); } while (0)
; #define LDA(dst, b, h) _Pragma("unroll") for (int m = 0; m < 4; ++m) _Pragma("unroll") for (int k = 0; k < 2; ++k) \
;     dst[m][k] = *reinterpret_cast<const bf16x8*>((char*)shm + abase + (((b) * 2 + (h)) * 16384 + (m * 2 + k) * 1024))
; #define LDB(dst, b, h) _Pragma("unroll") for (int n = 0; n < 2; ++n) _Pragma("unroll") for (int k = 0; k < 2; ++k) \
;     dst[n][k] = *reinterpret_cast<const bf16x8*>((char*)shm + bbase + (((b) * 2 + (h)) * 16384 + (n * 2 + k) * 1024))
; template <bool SWAP>
; __device__ __forceinline__ void gemm_main(const u16* __restrict__ A, const u16* __restrict__ Bt, int brow, int bcol,
;                                           u16* shm, f32x4 (&acc)[2][2][4][2]) {
;     ...
;     BAR; WAIT_L(0); MMA(1, 0, At, B0); BAR; SCHED;
;     STAGE(SB(0, 1), Bt, bcol + HALF, t + 2);
;     WAIT_V(6); BAR; MMA(1, 1, At, B1); BAR;
;     LDB(B0, 1, 0); SCHED; LDA(At, 1, 0); STAGE(SA(0, 1), A, brow + HALF, t + 2);
;     WAIT_L(8); BAR; WAIT_L(0); MMA(0, 0, At, B0); BAR; SCHED;
;     LDB(B1, 1, 1); STAGE(SB(1, 0), Bt, bcol, t + 3);
;     BAR; WAIT_L(0); MMA(0, 1, At, B1); BAR;
	v_add_u32_e32 v152, s29, v139
	v_lshl_add_u64 v[150:151], v[234:235], 0, s[70:71]
	v_readfirstlane_b32 s2, v152
	v_add_u32_e32 v152, 0x2000, v152
	s_mov_b32 m0, s2
	v_readfirstlane_b32 s2, v152
	global_load_lds_dwordx4 v[150:151], off
	v_lshl_add_u64 v[150:151], v[236:237], 0, s[70:71]
	s_mov_b32 m0, s2
	s_nop 0
	global_load_lds_dwordx4 v[150:151], off
	s_waitcnt vmcnt(6)
	s_barrier
	s_setprio 1
	v_mfma_f32_16x16x32_bf16 v[28:31], v[202:205], v[166:169], v[28:31]
	v_mfma_f32_16x16x32_bf16 v[24:27], v[224:227], v[166:169], v[24:27]
	v_mfma_f32_16x16x32_bf16 v[20:23], v[202:205], v[174:177], v[20:23]
	v_mfma_f32_16x16x32_bf16 v[16:19], v[224:227], v[174:177], v[16:19]
	v_mfma_f32_16x16x32_bf16 v[12:15], v[202:205], v[182:185], v[12:15]
	v_mfma_f32_16x16x32_bf16 v[8:11], v[224:227], v[182:185], v[8:11]
	v_mfma_f32_16x16x32_bf16 v[4:7], v[202:205], v[194:197], v[4:7]
	v_mfma_f32_16x16x32_bf16 v[0:3], v[224:227], v[194:197], v[0:3]
	v_mfma_f32_16x16x32_bf16 v[28:31], v[206:209], v[170:173], v[28:31]
	v_mfma_f32_16x16x32_bf16 v[24:27], v[228:231], v[170:173], v[24:27]
	v_mfma_f32_16x16x32_bf16 v[20:23], v[206:209], v[178:181], v[20:23]
	v_mfma_f32_16x16x32_bf16 v[16:19], v[228:231], v[178:181], v[16:19]
	v_mfma_f32_16x16x32_bf16 v[12:15], v[206:209], v[186:189], v[12:15]
	v_mfma_f32_16x16x32_bf16 v[8:11], v[228:231], v[186:189], v[8:11]
	v_mfma_f32_16x16x32_bf16 v[4:7], v[206:209], v[198:201], v[4:7]
	v_mfma_f32_16x16x32_bf16 v[0:3], v[228:231], v[198:201], v[0:3]
	s_setprio 0
	s_barrier
	ds_read_b128 v[150:153], v138 offset:32768
	ds_read_b128 v[154:157], v138 offset:33792
	ds_read_b128 v[158:161], v138 offset:34816
	ds_read_b128 v[162:165], v138 offset:35840
	v_add_u32_e32 v204, 0x4000, v192
	v_lshl_add_u64 v[202:203], v[190:191], 0, s[96:97]
	v_readfirstlane_b32 s2, v204
	v_add_u32_e32 v204, 0x6000, v192
	s_mov_b32 m0, s2
	v_readfirstlane_b32 s2, v204
	ds_read_b128 v[166:169], v137 offset:32768
	ds_read_b128 v[170:173], v137 offset:33792
	ds_read_b128 v[174:177], v137 offset:34816
	ds_read_b128 v[178:181], v137 offset:35840
	ds_read_b128 v[182:185], v137 offset:36864
	ds_read_b128 v[186:189], v137 offset:37888
	ds_read_b128 v[194:197], v137 offset:38912
	ds_read_b128 v[198:201], v137 offset:39936
	global_load_lds_dwordx4 v[202:203], off
	v_lshl_add_u64 v[202:203], v[232:233], 0, s[96:97]
	s_mov_b32 m0, s2
	s_nop 0
	global_load_lds_dwordx4 v[202:203], off
	s_waitcnt lgkmcnt(8)
	s_barrier
	s_waitcnt lgkmcnt(0)
	s_setprio 1
	v_mfma_f32_16x16x32_bf16 v[124:127], v[150:153], v[166:169], v[124:127]
	v_mfma_f32_16x16x32_bf16 v[120:123], v[158:161], v[166:169], v[120:123]
	v_mfma_f32_16x16x32_bf16 v[116:119], v[150:153], v[174:177], v[116:119]
	v_mfma_f32_16x16x32_bf16 v[112:115], v[158:161], v[174:177], v[112:115]
	v_mfma_f32_16x16x32_bf16 v[108:111], v[150:153], v[182:185], v[108:111]
	v_mfma_f32_16x16x32_bf16 v[104:107], v[158:161], v[182:185], v[104:107]
	v_mfma_f32_16x16x32_bf16 v[100:103], v[150:153], v[194:197], v[100:103]
	v_mfma_f32_16x16x32_bf16 v[96:99], v[158:161], v[194:197], v[96:99]
	v_mfma_f32_16x16x32_bf16 v[124:127], v[154:157], v[170:173], v[124:127]
	v_mfma_f32_16x16x32_bf16 v[120:123], v[162:165], v[170:173], v[120:123]
	v_mfma_f32_16x16x32_bf16 v[116:119], v[154:157], v[178:181], v[116:119]
	v_mfma_f32_16x16x32_bf16 v[112:115], v[162:165], v[178:181], v[112:115]
	v_mfma_f32_16x16x32_bf16 v[108:111], v[154:157], v[186:189], v[108:111]
	v_mfma_f32_16x16x32_bf16 v[104:107], v[162:165], v[186:189], v[104:107]
	v_mfma_f32_16x16x32_bf16 v[100:103], v[154:157], v[198:201], v[100:103]
	v_mfma_f32_16x16x32_bf16 v[96:99], v[162:165], v[198:201], v[96:99]
	s_setprio 0
	s_barrier
	v_add_u32_e32 v223, s30, v139
	v_lshl_add_u64 v[238:239], v[234:235], 0, s[34:35]
	v_readfirstlane_b32 s2, v223
	v_add_u32_e32 v223, 0x2000, v223
	s_mov_b32 m0, s2
	v_readfirstlane_b32 s2, v223
	ds_read_b128 v[202:205], v138 offset:49152
	ds_read_b128 v[206:209], v138 offset:50176
	ds_read_b128 v[224:227], v138 offset:51200
	ds_read_b128 v[228:231], v138 offset:52224
	global_load_lds_dwordx4 v[238:239], off
	v_lshl_add_u64 v[238:239], v[236:237], 0, s[34:35]
	s_mov_b32 m0, s2
	s_nop 0
	global_load_lds_dwordx4 v[238:239], off
	s_barrier
	s_waitcnt lgkmcnt(0)
	s_setprio 1
	v_mfma_f32_16x16x32_bf16 v[92:95], v[202:205], v[166:169], v[92:95]
	v_mfma_f32_16x16x32_bf16 v[88:91], v[224:227], v[166:169], v[88:91]
	v_mfma_f32_16x16x32_bf16 v[84:87], v[202:205], v[174:177], v[84:87]
	v_mfma_f32_16x16x32_bf16 v[80:83], v[224:227], v[174:177], v[80:83]
	v_mfma_f32_16x16x32_bf16 v[76:79], v[202:205], v[182:185], v[76:79]
	v_mfma_f32_16x16x32_bf16 v[72:75], v[224:227], v[182:185], v[72:75]
	v_mfma_f32_16x16x32_bf16 v[68:71], v[202:205], v[194:197], v[68:71]
	v_mfma_f32_16x16x32_bf16 v[64:67], v[224:227], v[194:197], v[64:67]
	v_mfma_f32_16x16x32_bf16 v[92:95], v[206:209], v[170:173], v[92:95]
	v_mfma_f32_16x16x32_bf16 v[88:91], v[228:231], v[170:173], v[88:91]
	v_mfma_f32_16x16x32_bf16 v[84:87], v[206:209], v[178:181], v[84:87]
	v_mfma_f32_16x16x32_bf16 v[80:83], v[228:231], v[178:181], v[80:83]
	v_mfma_f32_16x16x32_bf16 v[76:79], v[206:209], v[186:189], v[76:79]
	v_mfma_f32_16x16x32_bf16 v[72:75], v[228:231], v[186:189], v[72:75]
	v_mfma_f32_16x16x32_bf16 v[68:71], v[206:209], v[198:201], v[68:71]
	v_mfma_f32_16x16x32_bf16 v[64:67], v[228:231], v[198:201], v[64:67]
	s_setprio 0
	s_barrier
; #define WAIT_V(n) asm volatile("s_waitcnt vmcnt(" #n ")" ::: "memory")
; #define WAIT_L(n) asm volatile("s_waitcnt lgkmcnt(" #n ")" ::: "memory")
; #define BAR __builtin_amdgcn_s_barrier()
; #define SCHED __builtin_amdgcn_sched_barrier(0)
; #define STAGE(P, BASE, br, kt) do { const char* _g = (const char*)((BASE) + (size_t)(br) * GK + (kt) * BK); \
;     __builtin_amdgcn_global_load_lds((const unsigned*)(_g + voff0), (unsigned*)((char*)(P) + tx * 16), 16, 0, 0); \
;     __builtin_amdgcn_global_load_lds((const unsigned*)(_g + voff1), (unsigned*)((char*)(P) + tx * 16 + 8192), 16, 0, 0); } while (0)
; #define LDA(dst, b, h) _Pragma("unroll") for (int m = 0; m < 4; ++m) _Pragma("unroll") for (int k = 0; k < 2; ++k) \
;     dst[m][k] = *reinterpret_cast<const bf16x8*>((char*)shm + abase + (((b) * 2 + (h)) * 16384 + (m * 2 + k) * 1024))
; #define LDB(dst, b, h) _Pragma("unroll") for (int n = 0; n < 2; ++n) _Pragma("unroll") for (int k = 0; k < 2; ++k) \
;     dst[n][k] = *reinterpret_cast<const bf16x8*>((char*)shm + bbase + (((b) * 2 + (h)) * 16384 + (n * 2 + k) * 1024))
; template <bool SWAP>
; __device__ __forceinline__ void gemm_main(const u16* __restrict__ A, const u16* __restrict__ Bt, int brow, int bcol,
;                                           u16* shm, f32x4 (&acc)[2][2][4][2]) {
;     ...
;     BAR; WAIT_L(0); MMA(0, 1, At, B1); BAR;
;     LDA(At, 1, 1); STAGE(SA(1, 0), A, brow, t + 3);
;     BAR; WAIT_L(0); MMA(1, 0, At, B0); BAR; SCHED;
;     STAGE(SB(1, 1), Bt, bcol + HALF, t + 3);
;     WAIT_V(6); BAR; MMA(1, 1, At, B1); BAR;
;   }
;   { LDB(B0, 0, 0); LDA(At, 0, 0); STAGE(SA(1, 1), A, brow + HALF, nt - 1);
;     BAR; WAIT_L(0); MMA(0, 0, At, B0); BAR;
	ds_read_b128 v[166:169], v137 offset:49152
	ds_read_b128 v[170:173], v137 offset:50176
	ds_read_b128 v[174:177], v137 offset:51200
	ds_read_b128 v[178:181], v137 offset:52224
	ds_read_b128 v[182:185], v137 offset:53248
	ds_read_b128 v[186:189], v137 offset:54272
	ds_read_b128 v[194:197], v137 offset:55296
	ds_read_b128 v[198:201], v137 offset:56320
	v_add_u32_e32 v223, 0x8000, v192
	v_add_u32_e32 v192, 0xa000, v192
	v_readfirstlane_b32 s2, v223
	v_lshl_add_u64 v[190:191], v[190:191], 0, s[36:37]
	s_mov_b32 m0, s2
	v_readfirstlane_b32 s2, v192
	global_load_lds_dwordx4 v[190:191], off
	v_lshl_add_u64 v[190:191], v[232:233], 0, s[36:37]
	s_mov_b32 m0, s2
	s_nop 0
	global_load_lds_dwordx4 v[190:191], off
	s_barrier
	s_waitcnt lgkmcnt(0)
	s_setprio 1
	v_mfma_f32_16x16x32_bf16 v[60:63], v[150:153], v[166:169], v[60:63]
	v_mfma_f32_16x16x32_bf16 v[56:59], v[158:161], v[166:169], v[56:59]
	v_mfma_f32_16x16x32_bf16 v[52:55], v[150:153], v[174:177], v[52:55]
	v_mfma_f32_16x16x32_bf16 v[48:51], v[158:161], v[174:177], v[48:51]
	v_mfma_f32_16x16x32_bf16 v[44:47], v[150:153], v[182:185], v[44:47]
	v_mfma_f32_16x16x32_bf16 v[40:43], v[158:161], v[182:185], v[40:43]
	v_mfma_f32_16x16x32_bf16 v[36:39], v[150:153], v[194:197], v[36:39]
	v_mfma_f32_16x16x32_bf16 v[32:35], v[158:161], v[194:197], v[32:35]
	v_mfma_f32_16x16x32_bf16 v[60:63], v[154:157], v[170:173], v[60:63]
	v_mfma_f32_16x16x32_bf16 v[56:59], v[162:165], v[170:173], v[56:59]
	v_mfma_f32_16x16x32_bf16 v[52:55], v[154:157], v[178:181], v[52:55]
	v_mfma_f32_16x16x32_bf16 v[48:51], v[162:165], v[178:181], v[48:51]
	v_mfma_f32_16x16x32_bf16 v[44:47], v[154:157], v[186:189], v[44:47]
	v_mfma_f32_16x16x32_bf16 v[40:43], v[162:165], v[186:189], v[40:43]
	v_mfma_f32_16x16x32_bf16 v[36:39], v[154:157], v[198:201], v[36:39]
	v_mfma_f32_16x16x32_bf16 v[32:35], v[162:165], v[198:201], v[32:35]
	s_setprio 0
	s_barrier
	v_add_u32_e32 v152, s31, v139
	v_lshl_add_u64 v[150:151], v[234:235], 0, s[64:65]
	v_readfirstlane_b32 s2, v152
	v_add_u32_e32 v152, 0x2000, v152
	s_mov_b32 m0, s2
	v_readfirstlane_b32 s2, v152
	global_load_lds_dwordx4 v[150:151], off
	v_lshl_add_u64 v[150:151], v[236:237], 0, s[64:65]
	s_mov_b32 m0, s2
	s_nop 0
	global_load_lds_dwordx4 v[150:151], off
	s_waitcnt vmcnt(6)
	s_barrier
	s_setprio 1
	v_mfma_f32_16x16x32_bf16 v[28:31], v[202:205], v[166:169], v[28:31]
	v_mfma_f32_16x16x32_bf16 v[24:27], v[224:227], v[166:169], v[24:27]
	v_mfma_f32_16x16x32_bf16 v[20:23], v[202:205], v[174:177], v[20:23]
	v_mfma_f32_16x16x32_bf16 v[16:19], v[224:227], v[174:177], v[16:19]
	v_mfma_f32_16x16x32_bf16 v[12:15], v[202:205], v[182:185], v[12:15]
	v_mfma_f32_16x16x32_bf16 v[8:11], v[224:227], v[182:185], v[8:11]
	v_mfma_f32_16x16x32_bf16 v[4:7], v[202:205], v[194:197], v[4:7]
	v_mfma_f32_16x16x32_bf16 v[0:3], v[224:227], v[194:197], v[0:3]
	v_mfma_f32_16x16x32_bf16 v[28:31], v[206:209], v[170:173], v[28:31]
	v_mfma_f32_16x16x32_bf16 v[24:27], v[228:231], v[170:173], v[24:27]
	v_mfma_f32_16x16x32_bf16 v[20:23], v[206:209], v[178:181], v[20:23]
	v_mfma_f32_16x16x32_bf16 v[16:19], v[228:231], v[178:181], v[16:19]
	v_mfma_f32_16x16x32_bf16 v[12:15], v[206:209], v[186:189], v[12:15]
	v_mfma_f32_16x16x32_bf16 v[8:11], v[228:231], v[186:189], v[8:11]
	v_mfma_f32_16x16x32_bf16 v[4:7], v[206:209], v[198:201], v[4:7]
	v_mfma_f32_16x16x32_bf16 v[0:3], v[228:231], v[198:201], v[0:3]
	s_setprio 0
	s_add_i32 s1, s1, 2
	v_lshl_add_u64 v[128:129], v[128:129], 0, s[74:75]
	v_lshl_add_u64 v[130:131], v[130:131], 0, s[74:75]
	v_lshl_add_u64 v[132:133], v[132:133], 0, s[74:75]
	s_cmp_lt_u32 s1, 28
	v_lshl_add_u64 v[134:135], v[134:135], 0, s[74:75]
	s_barrier
	s_cbranch_scc1 .LBB0_436
	v_lshlrev_b32_e32 v128, 3, v142
	v_lshlrev_b32_e32 v129, 5, v142
	v_and_b32_e32 v128, 0xffff0, v128
	v_and_b32_e32 v129, 32, v129
	s_or_b32 s2, s0, 0x80
	v_add_u32_e32 v129, v129, v144
	v_add_lshl_u32 v128, v143, v128, 12
	s_ashr_i32 s3, s2, 31
	v_lshl_add_u32 v192, v129, 1, v128
	v_lshlrev_b32_e32 v128, 3, v145
	v_lshlrev_b32_e32 v129, 5, v145
	s_lshl_b64 s[2:3], s[2:3], 12
	v_and_b32_e32 v128, 0xffff0, v128
	v_and_b32_e32 v129, 32, v129
	s_add_u32 s2, s16, s2
	v_add_u32_e32 v129, v129, v147
	v_add_lshl_u32 v128, v146, v128, 12
	s_addc_u32 s3, s17, s3
	v_lshl_add_u32 v146, v129, 1, v128
	v_mov_b32_e32 v147, v193
	v_lshl_add_u64 v[186:187], s[2:3], 0, v[192:193]
	s_mov_b64 s[8:9], 0xf80
	v_readfirstlane_b32 s1, v148
	v_lshl_add_u64 v[186:187], v[186:187], 0, s[8:9]
	s_mov_b32 m0, s1
	v_lshl_add_u64 v[146:147], s[2:3], 0, v[146:147]
	v_readfirstlane_b32 s1, v149
	ds_read_b128 v[128:131], v138
	ds_read_b128 v[132:135], v138 offset:1024
	ds_read_b128 v[142:145], v138 offset:2048
	ds_read_b128 v[150:153], v138 offset:3072
	ds_read_b128 v[154:157], v137
	ds_read_b128 v[158:161], v137 offset:1024
	ds_read_b128 v[162:165], v137 offset:2048
	ds_read_b128 v[166:169], v137 offset:3072
	ds_read_b128 v[170:173], v137 offset:4096
	ds_read_b128 v[174:177], v137 offset:5120
	ds_read_b128 v[178:181], v137 offset:6144
	ds_read_b128 v[182:185], v137 offset:7168
	global_load_lds_dwordx4 v[186:187], off
	v_lshl_add_u64 v[146:147], v[146:147], 0, s[8:9]
	s_mov_b32 m0, s1
	s_nop 0
	global_load_lds_dwordx4 v[146:147], off
	s_barrier
; #define WAIT_V(n) asm volatile("s_waitcnt vmcnt(" #n ")" ::: "memory")
; #define WAIT_L(n) asm volatile("s_waitcnt lgkmcnt(" #n ")" ::: "memory")
; #define BAR __builtin_amdgcn_s_barrier()
; #define STAGE(P, BASE, br, kt) do { const char* _g = (const char*)((BASE) + (size_t)(br) * GK + (kt) * BK); \
;     __builtin_amdgcn_global_load_lds((const unsigned*)(_g + voff0), (unsigned*)((char*)(P) + tx * 16), 16, 0, 0); \
;     __builtin_amdgcn_global_load_lds((const unsigned*)(_g + voff1), (unsigned*)((char*)(P) + tx * 16 + 8192), 16, 0, 0); } while (0)
; #define LDA(dst, b, h) _Pragma("unroll") for (int m = 0; m < 4; ++m) _Pragma("unroll") for (int k = 0; k < 2; ++k) \
;     dst[m][k] = *reinterpret_cast<const bf16x8*>((char*)shm + abase + (((b) * 2 + (h)) * 16384 + (m * 2 + k) * 1024))
; #define LDB(dst, b, h) _Pragma("unroll") for (int n = 0; n < 2; ++n) _Pragma("unroll") for (int k = 0; k < 2; ++k) \
;     dst[n][k] = *reinterpret_cast<const bf16x8*>((char*)shm + bbase + (((b) * 2 + (h)) * 16384 + (n * 2 + k) * 1024))
; template <bool SWAP>
; __device__ __forceinline__ void gemm_main(const u16* __restrict__ A, const u16* __restrict__ Bt, int brow, int bcol,
;                                           u16* shm, f32x4 (&acc)[2][2][4][2]) {
;     ...
;   { LDB(B0, 0, 0); LDA(At, 0, 0); STAGE(SA(1, 1), A, brow + HALF, nt - 1);
;     BAR; WAIT_L(0); MMA(0, 0, At, B0); BAR;
;     LDB(B1, 0, 1); BAR; WAIT_L(0); MMA(0, 1, At, B1); BAR;
;     LDA(At, 0, 1); WAIT_V(4); BAR; WAIT_L(0); MMA(1, 0, At, B0); MMA(1, 1, At, B1); BAR; }
;   { LDB(B0, 1, 0); LDA(At, 1, 0); WAIT_V(2); BAR; WAIT_L(0); MMA(0, 0, At, B0); BAR;
	s_waitcnt lgkmcnt(0)
	s_setprio 1
	s_waitcnt lgkmcnt(0)
	v_mfma_f32_16x16x32_bf16 v[124:127], v[128:131], v[154:157], v[124:127]
	v_mfma_f32_16x16x32_bf16 v[112:115], v[142:145], v[162:165], v[112:115]
	v_mfma_f32_16x16x32_bf16 v[104:107], v[142:145], v[170:173], v[104:107]
	v_mfma_f32_16x16x32_bf16 v[96:99], v[142:145], v[178:181], v[96:99]
	v_mfma_f32_16x16x32_bf16 v[124:127], v[132:135], v[158:161], v[124:127]
	v_mfma_f32_16x16x32_bf16 v[120:123], v[142:145], v[154:157], v[120:123]
	v_mfma_f32_16x16x32_bf16 v[116:119], v[128:131], v[162:165], v[116:119]
	v_mfma_f32_16x16x32_bf16 v[112:115], v[150:153], v[166:169], v[112:115]
	v_mfma_f32_16x16x32_bf16 v[108:111], v[128:131], v[170:173], v[108:111]
	v_mfma_f32_16x16x32_bf16 v[104:107], v[150:153], v[174:177], v[104:107]
	v_mfma_f32_16x16x32_bf16 v[100:103], v[128:131], v[178:181], v[100:103]
	v_mfma_f32_16x16x32_bf16 v[96:99], v[150:153], v[182:185], v[96:99]
	v_mfma_f32_16x16x32_bf16 v[146:149], v[150:153], v[158:161], v[120:123]
	v_mfma_f32_16x16x32_bf16 v[186:189], v[132:135], v[166:169], v[116:119]
	v_mfma_f32_16x16x32_bf16 v[194:197], v[132:135], v[174:177], v[108:111]
	v_mfma_f32_16x16x32_bf16 v[198:201], v[132:135], v[182:185], v[100:103]
	s_setprio 0
	s_barrier
	s_nop 0
	ds_read_b128 v[100:103], v138 offset:16384
	ds_read_b128 v[108:111], v138 offset:17408
	ds_read_b128 v[116:119], v138 offset:18432
	ds_read_b128 v[120:123], v138 offset:19456
	s_barrier
	s_waitcnt lgkmcnt(0)
	s_setprio 1
	s_waitcnt lgkmcnt(0)
	v_mfma_f32_16x16x32_bf16 v[88:91], v[116:119], v[154:157], v[88:91]
	v_mfma_f32_16x16x32_bf16 v[80:83], v[116:119], v[162:165], v[80:83]
	v_mfma_f32_16x16x32_bf16 v[72:75], v[116:119], v[170:173], v[72:75]
	v_mfma_f32_16x16x32_bf16 v[64:67], v[116:119], v[178:181], v[64:67]
	v_mfma_f32_16x16x32_bf16 v[92:95], v[100:103], v[154:157], v[92:95]
	v_mfma_f32_16x16x32_bf16 v[88:91], v[120:123], v[158:161], v[88:91]
	v_mfma_f32_16x16x32_bf16 v[84:87], v[100:103], v[162:165], v[84:87]
	v_mfma_f32_16x16x32_bf16 v[80:83], v[120:123], v[166:169], v[80:83]
	v_mfma_f32_16x16x32_bf16 v[76:79], v[100:103], v[170:173], v[76:79]
	v_mfma_f32_16x16x32_bf16 v[72:75], v[120:123], v[174:177], v[72:75]
	v_mfma_f32_16x16x32_bf16 v[68:71], v[100:103], v[178:181], v[68:71]
	v_mfma_f32_16x16x32_bf16 v[64:67], v[120:123], v[182:185], v[64:67]
	v_mfma_f32_16x16x32_bf16 v[202:205], v[108:111], v[158:161], v[92:95]
	v_mfma_f32_16x16x32_bf16 v[154:157], v[108:111], v[166:169], v[84:87]
	v_mfma_f32_16x16x32_bf16 v[158:161], v[108:111], v[174:177], v[76:79]
	v_mfma_f32_16x16x32_bf16 v[162:165], v[108:111], v[182:185], v[68:71]
	s_setprio 0
	s_barrier
	s_nop 0
	ds_read_b128 v[68:71], v137 offset:16384
	ds_read_b128 v[76:79], v137 offset:17408
	ds_read_b128 v[84:87], v137 offset:18432
	ds_read_b128 v[92:95], v137 offset:19456
	ds_read_b128 v[166:169], v137 offset:20480
	ds_read_b128 v[170:173], v137 offset:21504
	ds_read_b128 v[174:177], v137 offset:22528
	ds_read_b128 v[178:181], v137 offset:23552
	s_waitcnt vmcnt(4)
	s_barrier
	s_waitcnt lgkmcnt(0)
	s_setprio 1
	s_waitcnt lgkmcnt(0)
	v_mfma_f32_16x16x32_bf16 v[60:63], v[128:131], v[68:71], v[60:63]
	v_mfma_f32_16x16x32_bf16 v[56:59], v[142:145], v[68:71], v[56:59]
	v_mfma_f32_16x16x32_bf16 v[48:51], v[142:145], v[84:87], v[48:51]
	v_mfma_f32_16x16x32_bf16 v[40:43], v[142:145], v[166:169], v[40:43]
	v_mfma_f32_16x16x32_bf16 v[32:35], v[142:145], v[174:177], v[32:35]
	v_mfma_f32_16x16x32_bf16 v[60:63], v[132:135], v[76:79], v[60:63]
	v_mfma_f32_16x16x32_bf16 v[56:59], v[150:153], v[76:79], v[56:59]
	v_mfma_f32_16x16x32_bf16 v[52:55], v[128:131], v[84:87], v[52:55]
	v_mfma_f32_16x16x32_bf16 v[48:51], v[150:153], v[92:95], v[48:51]
	v_mfma_f32_16x16x32_bf16 v[44:47], v[128:131], v[166:169], v[44:47]
	v_mfma_f32_16x16x32_bf16 v[40:43], v[150:153], v[170:173], v[40:43]
	v_mfma_f32_16x16x32_bf16 v[36:39], v[128:131], v[174:177], v[36:39]
	v_mfma_f32_16x16x32_bf16 v[32:35], v[150:153], v[178:181], v[32:35]
	v_mfma_f32_16x16x32_bf16 v[182:185], v[132:135], v[92:95], v[52:55]
	v_mfma_f32_16x16x32_bf16 v[206:209], v[132:135], v[170:173], v[44:47]
	v_mfma_f32_16x16x32_bf16 v[128:131], v[132:135], v[178:181], v[36:39]
	s_setprio 0
	s_setprio 1
	v_mfma_f32_16x16x32_bf16 v[24:27], v[116:119], v[68:71], v[24:27]
	v_mfma_f32_16x16x32_bf16 v[16:19], v[116:119], v[84:87], v[16:19]
	v_mfma_f32_16x16x32_bf16 v[8:11], v[116:119], v[166:169], v[8:11]
	v_mfma_f32_16x16x32_bf16 v[0:3], v[116:119], v[174:177], v[0:3]
	v_mfma_f32_16x16x32_bf16 v[28:31], v[100:103], v[68:71], v[28:31]
	v_mfma_f32_16x16x32_bf16 v[24:27], v[120:123], v[76:79], v[24:27]
	v_mfma_f32_16x16x32_bf16 v[20:23], v[100:103], v[84:87], v[20:23]
	v_mfma_f32_16x16x32_bf16 v[16:19], v[120:123], v[92:95], v[16:19]
	v_mfma_f32_16x16x32_bf16 v[12:15], v[100:103], v[166:169], v[12:15]
	v_mfma_f32_16x16x32_bf16 v[8:11], v[120:123], v[170:173], v[8:11]
	v_mfma_f32_16x16x32_bf16 v[4:7], v[100:103], v[174:177], v[4:7]
	v_mfma_f32_16x16x32_bf16 v[0:3], v[120:123], v[178:181], v[0:3]
	v_mfma_f32_16x16x32_bf16 v[132:135], v[108:111], v[76:79], v[28:31]
	v_mfma_f32_16x16x32_bf16 v[142:145], v[108:111], v[92:95], v[20:23]
	v_mfma_f32_16x16x32_bf16 v[150:153], v[108:111], v[170:173], v[12:15]
	v_mfma_f32_16x16x32_bf16 v[166:169], v[108:111], v[178:181], v[4:7]
	s_setprio 0
	s_barrier
	s_nop 0
	ds_read_b128 v[4:7], v138 offset:32768
	ds_read_b128 v[12:15], v138 offset:33792
	ds_read_b128 v[170:173], v138 offset:34816
	ds_read_b128 v[174:177], v138 offset:35840
	ds_read_b128 v[20:23], v137 offset:32768
	ds_read_b128 v[28:31], v137 offset:33792
	ds_read_b128 v[36:39], v137 offset:34816
	ds_read_b128 v[44:47], v137 offset:35840
	ds_read_b128 v[52:55], v137 offset:36864
	ds_read_b128 v[178:181], v137 offset:37888
	ds_read_b128 v[224:227], v137 offset:38912
	ds_read_b128 v[228:231], v137 offset:39936
	s_waitcnt vmcnt(2)
	s_barrier
; #define WAIT_V(n) asm volatile("s_waitcnt vmcnt(" #n ")" ::: "memory")
; #define WAIT_L(n) asm volatile("s_waitcnt lgkmcnt(" #n ")" ::: "memory")
; #define BAR __builtin_amdgcn_s_barrier()
; #define LDA(dst, b, h) _Pragma("unroll") for (int m = 0; m < 4; ++m) _Pragma("unroll") for (int k = 0; k < 2; ++k) \
;     dst[m][k] = *reinterpret_cast<const bf16x8*>((char*)shm + abase + (((b) * 2 + (h)) * 16384 + (m * 2 + k) * 1024))
; #define LDB(dst, b, h) _Pragma("unroll") for (int n = 0; n < 2; ++n) _Pragma("unroll") for (int k = 0; k < 2; ++k) \
;     dst[n][k] = *reinterpret_cast<const bf16x8*>((char*)shm + bbase + (((b) * 2 + (h)) * 16384 + (n * 2 + k) * 1024))
; template <bool SWAP>
; __device__ __forceinline__ void gemm_main(const u16* __restrict__ A, const u16* __restrict__ Bt, int brow, int bcol,
;                                           u16* shm, f32x4 (&acc)[2][2][4][2]) {
;     ...
;   { LDB(B0, 1, 0); LDA(At, 1, 0); WAIT_V(2); BAR; WAIT_L(0); MMA(0, 0, At, B0); BAR;
;     LDB(B1, 1, 1); WAIT_V(0); BAR; WAIT_L(0); MMA(0, 1, At, B1); BAR;
;     LDA(At, 1, 1); BAR; WAIT_L(0); MMA(1, 0, At, B0); MMA(1, 1, At, B1); BAR; }
;   if (wr == 0) BAR;
	s_waitcnt lgkmcnt(0)
	s_setprio 1
	s_waitcnt lgkmcnt(0)
	v_mfma_f32_16x16x32_bf16 v[68:71], v[4:7], v[20:23], v[124:127]
	v_mfma_f32_16x16x32_bf16 v[120:123], v[12:15], v[28:31], v[68:71]
	v_mfma_f32_16x16x32_bf16 v[68:71], v[170:173], v[20:23], v[146:149]
	v_mfma_f32_16x16x32_bf16 v[116:119], v[174:177], v[28:31], v[68:71]
	v_mfma_f32_16x16x32_bf16 v[68:71], v[4:7], v[36:39], v[186:189]
	v_mfma_f32_16x16x32_bf16 v[108:111], v[12:15], v[44:47], v[68:71]
	v_mfma_f32_16x16x32_bf16 v[68:71], v[170:173], v[36:39], v[112:115]
	v_mfma_f32_16x16x32_bf16 v[100:103], v[174:177], v[44:47], v[68:71]
	v_mfma_f32_16x16x32_bf16 v[68:71], v[4:7], v[52:55], v[194:197]
	v_mfma_f32_16x16x32_bf16 v[92:95], v[12:15], v[178:181], v[68:71]
	v_mfma_f32_16x16x32_bf16 v[68:71], v[170:173], v[52:55], v[104:107]
	v_mfma_f32_16x16x32_bf16 v[84:87], v[174:177], v[178:181], v[68:71]
	v_mfma_f32_16x16x32_bf16 v[68:71], v[4:7], v[224:227], v[198:201]
	v_mfma_f32_16x16x32_bf16 v[76:79], v[12:15], v[228:231], v[68:71]
	v_mfma_f32_16x16x32_bf16 v[68:71], v[170:173], v[224:227], v[96:99]
	v_mfma_f32_16x16x32_bf16 v[68:71], v[174:177], v[228:231], v[68:71]
	s_setprio 0
	s_barrier
	ds_read_b128 v[146:149], v138 offset:49152
	ds_read_b128 v[186:189], v138 offset:50176
	ds_read_b128 v[194:197], v138 offset:51200
	ds_read_b128 v[198:201], v138 offset:52224
	s_waitcnt vmcnt(0)
	s_barrier
	s_waitcnt lgkmcnt(0)
	s_setprio 1
	s_waitcnt lgkmcnt(0)
	v_mfma_f32_16x16x32_bf16 v[96:99], v[146:149], v[20:23], v[202:205]
	v_mfma_f32_16x16x32_bf16 v[20:23], v[194:197], v[20:23], v[88:91]
	v_mfma_f32_16x16x32_bf16 v[112:115], v[198:201], v[28:31], v[20:23]
	v_mfma_f32_16x16x32_bf16 v[20:23], v[146:149], v[36:39], v[154:157]
	v_mfma_f32_16x16x32_bf16 v[104:107], v[186:189], v[44:47], v[20:23]
	v_mfma_f32_16x16x32_bf16 v[20:23], v[194:197], v[36:39], v[80:83]
	v_mfma_f32_16x16x32_bf16 v[124:127], v[186:189], v[28:31], v[96:99]
	v_mfma_f32_16x16x32_bf16 v[96:99], v[198:201], v[44:47], v[20:23]
	v_mfma_f32_16x16x32_bf16 v[20:23], v[146:149], v[52:55], v[158:161]
	v_mfma_f32_16x16x32_bf16 v[88:91], v[186:189], v[178:181], v[20:23]
	v_mfma_f32_16x16x32_bf16 v[20:23], v[194:197], v[52:55], v[72:75]
	v_mfma_f32_16x16x32_bf16 v[80:83], v[198:201], v[178:181], v[20:23]
	v_mfma_f32_16x16x32_bf16 v[20:23], v[146:149], v[224:227], v[162:165]
	v_mfma_f32_16x16x32_bf16 v[72:75], v[186:189], v[228:231], v[20:23]
	v_mfma_f32_16x16x32_bf16 v[20:23], v[194:197], v[224:227], v[64:67]
	v_mfma_f32_16x16x32_bf16 v[64:67], v[198:201], v[228:231], v[20:23]
	s_setprio 0
	s_barrier
	ds_read_b128 v[154:157], v137 offset:49152
	ds_read_b128 v[158:161], v137 offset:50176
	ds_read_b128 v[162:165], v137 offset:51200
	ds_read_b128 v[178:181], v137 offset:52224
	ds_read_b128 v[202:205], v137 offset:53248
	ds_read_b128 v[224:227], v137 offset:54272
	ds_read_b128 v[228:231], v137 offset:55296
	ds_read_b128 v[232:235], v137 offset:56320
	s_barrier
	s_waitcnt lgkmcnt(0)
	s_setprio 1
	s_waitcnt lgkmcnt(0)
	v_mfma_f32_16x16x32_bf16 v[20:23], v[4:7], v[154:157], v[60:63]
	v_mfma_f32_16x16x32_bf16 v[60:63], v[12:15], v[158:161], v[20:23]
	v_mfma_f32_16x16x32_bf16 v[20:23], v[170:173], v[154:157], v[56:59]
	v_mfma_f32_16x16x32_bf16 v[52:55], v[174:177], v[158:161], v[20:23]
	v_mfma_f32_16x16x32_bf16 v[20:23], v[4:7], v[162:165], v[182:185]
	v_mfma_f32_16x16x32_bf16 v[44:47], v[12:15], v[178:181], v[20:23]
	v_mfma_f32_16x16x32_bf16 v[20:23], v[170:173], v[162:165], v[48:51]
	v_mfma_f32_16x16x32_bf16 v[36:39], v[174:177], v[178:181], v[20:23]
	v_mfma_f32_16x16x32_bf16 v[20:23], v[4:7], v[202:205], v[206:209]
	v_mfma_f32_16x16x32_bf16 v[4:7], v[4:7], v[228:231], v[128:131]
	v_mfma_f32_16x16x32_bf16 v[28:31], v[12:15], v[224:227], v[20:23]
	v_mfma_f32_16x16x32_bf16 v[20:23], v[170:173], v[202:205], v[40:43]
	v_mfma_f32_16x16x32_bf16 v[12:15], v[12:15], v[232:235], v[4:7]
	v_mfma_f32_16x16x32_bf16 v[4:7], v[170:173], v[228:231], v[32:35]
	v_mfma_f32_16x16x32_bf16 v[20:23], v[174:177], v[224:227], v[20:23]
	v_mfma_f32_16x16x32_bf16 v[4:7], v[174:177], v[232:235], v[4:7]
	s_setprio 0
	s_setprio 1
	v_mfma_f32_16x16x32_bf16 v[32:35], v[146:149], v[154:157], v[132:135]
	v_mfma_f32_16x16x32_bf16 v[24:27], v[194:197], v[154:157], v[24:27]
	v_mfma_f32_16x16x32_bf16 v[16:19], v[194:197], v[162:165], v[16:19]
	v_mfma_f32_16x16x32_bf16 v[56:59], v[186:189], v[158:161], v[32:35]
	v_mfma_f32_16x16x32_bf16 v[48:51], v[198:201], v[158:161], v[24:27]
	v_mfma_f32_16x16x32_bf16 v[24:27], v[146:149], v[162:165], v[142:145]
	v_mfma_f32_16x16x32_bf16 v[32:35], v[198:201], v[178:181], v[16:19]
	v_mfma_f32_16x16x32_bf16 v[16:19], v[146:149], v[202:205], v[150:153]
	v_mfma_f32_16x16x32_bf16 v[8:11], v[194:197], v[202:205], v[8:11]
	v_mfma_f32_16x16x32_bf16 v[40:43], v[186:189], v[178:181], v[24:27]
	v_mfma_f32_16x16x32_bf16 v[24:27], v[186:189], v[224:227], v[16:19]
	v_mfma_f32_16x16x32_bf16 v[16:19], v[198:201], v[224:227], v[8:11]
	v_mfma_f32_16x16x32_bf16 v[8:11], v[146:149], v[228:231], v[166:169]
	v_mfma_f32_16x16x32_bf16 v[0:3], v[194:197], v[228:231], v[0:3]
	v_mfma_f32_16x16x32_bf16 v[8:11], v[186:189], v[232:235], v[8:11]
	v_mfma_f32_16x16x32_bf16 v[0:3], v[198:201], v[232:235], v[0:3]
	s_setprio 0
	s_movk_i32 s1, 0x100
	v_cmp_gt_u32_e32 vcc, s1, v136
	s_barrier
	s_and_saveexec_b64 s[8:9], vcc
	s_cbranch_execz .LBB0_439
	s_barrier
